# P3 cmp pacing stride 2 (dynamic cmp tickets drained in the first half) on the LDS-staged cmp task version
# speedup vs baseline: 1.0002x; 1.0002x over previous
; DI void cmp_task(const bf16_t* Z, const bf16_t* KCC, const bf16_t* VCT, bf16_t* OCMP, unsigned* selm, int b, int hk, int tg, int lane) {
;     ...
; #pragma unroll
;         for (int mm = 0; mm < 4; ++mm) {
;             const int jm = 8 * g + 2 * mm + h; const float v = mine[mm]; int rank = 0;
; #pragma unroll
;             for (int T = 0; T < 4; ++T)
; #pragma unroll
;                 for (int m2 = 0; m2 < 4; ++m2) { const int je = 8 * T + 2 * m2;
;                     rank += (ev[T][m2] > v || (ev[T][m2] == v && je < jm)) ? 1 : 0; rank += (od[T][m2] > v || (od[T][m2] == v && je + 1 < jm)) ? 1 : 0; }
;             if (v >= 0.f && rank < 5) word |= 1u << jm;
; __global__ void __launch_bounds__(NTHR, 2) fwd_kernel(Args a) {
;     ...
;     {
;         const int nrow = (MTOK - gw + NGW - 1) / NGW, ncmp = (8192 - gw + NGW - 1) / NGW;
;         const int stride = nrow > 0 && ncmp > 0 ? (nrow / ncmp > 0 ? nrow / ncmp : 1) : 1, phase = ((wave >> 2) * (stride >> 1) + (wave & 1)) % stride;
;         int ci = 0;
;         for (int i = 0; i < nrow || ci < ncmp; ++i) {
;             if (ci < ncmp && (i >= nrow || (i % stride) == phase)) { const int task = gw + ci * NGW; ++ci;
.LBB0_474:
	s_mov_b32 s69, 2
	v_cvt_f32_u32_e32 v1, s69
	s_add_u32 s21, s18, 0x6000000
	s_addc_u32 s68, s19, 0
	s_add_u32 s12, s18, 0x6800000
	v_rcp_iflag_f32_e32 v1, v1
	s_addc_u32 s13, s19, 0
	s_or_b64 s[4:5], s[8:9], s[10:11]
	s_andn2_b64 vcc, exec, s[4:5]
	v_mul_f32_e32 v1, 0x4f7ffffe, v1
	v_cvt_u32_f32_e32 v1, v1
	s_nop 0
	v_readfirstlane_b32 s59, v1
	s_cbranch_vccnz .LBB0_659
	v_lshlrev_b32_e32 v1, 6, v133
	v_or_b32_e32 v37, 47, v1
	v_or_b32_e32 v46, 31, v1
	v_or_b32_e32 v117, 63, v1
	v_add_u32_e32 v119, 0x4f, v1
	v_or_b32_e32 v39, 0xaf, v1
	v_or_b32_e32 v48, 0x9f, v1
	v_or_b32_e32 v202, 0xbf, v1
	v_add_u32_e32 v203, 0xcf, v1
	v_or_b32_e32 v47, 0x12f, v1
	v_or_b32_e32 v50, 0x11f, v1
	v_or_b32_e32 v204, 0x13f, v1
	v_add_u32_e32 v205, 0x14f, v1
	v_or_b32_e32 v49, 0x1af, v1
	v_or_b32_e32 v52, 0x19f, v1
	v_or_b32_e32 v206, 0x1bf, v1
	v_add_u32_e32 v207, 0x1cf, v1
	v_or_b32_e32 v51, 0x22f, v1
	v_or_b32_e32 v54, 0x21f, v1
	v_or_b32_e32 v208, 0x23f, v1
	v_add_u32_e32 v209, 0x24f, v1
	v_or_b32_e32 v53, 0x2af, v1
	v_or_b32_e32 v56, 0x29f, v1
	v_or_b32_e32 v210, 0x2bf, v1
	v_add_u32_e32 v211, 0x2cf, v1
	v_or_b32_e32 v55, 0x32f, v1
	v_or_b32_e32 v58, 0x31f, v1
	v_or_b32_e32 v212, 0x33f, v1
	v_add_u32_e32 v213, 0x34f, v1
	v_or_b32_e32 v57, 0x3af, v1
	v_or_b32_e32 v60, 0x39f, v1
	v_or_b32_e32 v216, 0x3bf, v1
	v_add_u32_e32 v217, 0x3cf, v1
	v_or_b32_e32 v59, 0x42f, v1
	v_or_b32_e32 v62, 0x41f, v1
	v_or_b32_e32 v218, 0x43f, v1
	v_add_u32_e32 v219, 0x44f, v1
	v_or_b32_e32 v61, 0x4af, v1
	v_or_b32_e32 v64, 0x49f, v1
	v_or_b32_e32 v220, 0x4bf, v1
	v_add_u32_e32 v221, 0x4cf, v1
	v_or_b32_e32 v63, 0x52f, v1
	v_or_b32_e32 v66, 0x51f, v1
	v_or_b32_e32 v222, 0x53f, v1
	v_add_u32_e32 v223, 0x54f, v1
	v_or_b32_e32 v65, 0x5af, v1
	v_or_b32_e32 v68, 0x59f, v1
	v_or_b32_e32 v224, 0x5bf, v1
	v_add_u32_e32 v225, 0x5cf, v1
	v_or_b32_e32 v67, 0x62f, v1
	v_or_b32_e32 v70, 0x61f, v1
	v_or_b32_e32 v226, 0x63f, v1
	v_add_u32_e32 v227, 0x64f, v1
	v_or_b32_e32 v69, 0x6af, v1
	v_or_b32_e32 v72, 0x69f, v1
	v_or_b32_e32 v228, 0x6bf, v1
	v_add_u32_e32 v229, 0x6cf, v1
	v_or_b32_e32 v71, 0x72f, v1
	v_or_b32_e32 v74, 0x71f, v1
	v_or_b32_e32 v230, 0x73f, v1
	v_add_u32_e32 v231, 0x74f, v1
	v_or_b32_e32 v73, 0x7af, v1
	v_or_b32_e32 v76, 0x79f, v1
	v_or_b32_e32 v232, 0x7bf, v1
	v_add_u32_e32 v233, 0x7cf, v1
	v_lshl_or_b32 v1, v214, 3, v133
	v_cmp_lt_u32_e64 s[16:17], 2, v1
	v_cmp_lt_u32_e64 s[26:27], 10, v1
	v_cmp_lt_u32_e64 s[38:39], 18, v1
	v_writelane_b32 v253, s16, 6
	v_mov_b32_e32 v43, 0
	v_lshlrev_b32_e32 v40, 1, v139
	v_writelane_b32 v253, s17, 7
	v_cmp_lt_u32_e64 s[16:17], 4, v1
	v_mov_b32_e32 v41, v43
	v_or_b32_e32 v2, 2, v1
	v_writelane_b32 v253, s16, 8
	v_lshl_add_u64 v[44:45], s[48:49], 0, v[40:41]
	v_cmp_lt_u32_e64 s[48:49], 4, v2
	v_writelane_b32 v253, s17, 9
	v_cmp_lt_u32_e64 s[16:17], 6, v1
	s_lshr_b32 s4, s78, 8
	s_lshr_b32 s5, s69, 1
	v_writelane_b32 v253, s16, 10
	s_mul_i32 s4, s5, s4
	s_bfe_u32 s5, s78, 0x10006
	v_writelane_b32 v253, s17, 11
	v_cmp_lt_u32_e64 s[16:17], 8, v1
	s_add_i32 s4, s4, s5
	s_sub_i32 s5, 0, s69
	v_writelane_b32 v253, s16, 12
	s_mul_i32 s5, s5, s59
	s_mul_hi_u32 s5, s59, s5
	v_writelane_b32 v253, s17, 13
	v_writelane_b32 v253, s26, 14
	s_add_i32 s59, s59, s5
	s_mul_hi_u32 s5, s4, s59
	v_writelane_b32 v253, s27, 15
	v_cmp_lt_u32_e64 s[26:27], 12, v1
	s_mul_i32 s5, s5, s69
	s_sub_i32 s4, s4, s5
	v_writelane_b32 v253, s26, 16
	s_sub_i32 s5, s4, s69
	s_cmp_ge_u32 s4, s69
	v_writelane_b32 v253, s27, 17
	v_cmp_lt_u32_e64 s[26:27], 14, v1
	s_cselect_b32 s4, s5, s4
	s_sub_i32 s5, s4, s69
	v_writelane_b32 v253, s26, 18
	v_cmp_ne_u32_e64 s[6:7], 0, v1
	v_lshlrev_b32_e64 v237, v1, 1
	v_writelane_b32 v253, s27, 19
	v_cmp_lt_u32_e64 s[26:27], 16, v1
	v_lshlrev_b32_e64 v238, v1, 4
	v_lshlrev_b32_e64 v239, v1, 16
	v_writelane_b32 v253, s26, 20
	v_lshlrev_b32_e64 v240, v1, 64
	s_cmp_ge_u32 s4, s69
	v_writelane_b32 v253, s27, 21
	v_writelane_b32 v253, s38, 22
	v_mov_b32_e32 v139, v43
	v_lshlrev_b32_e32 v88, 2, v135
	v_writelane_b32 v253, s39, 23
	v_cmp_lt_u32_e64 s[38:39], 20, v1
	v_lshlrev_b32_e32 v241, 2, v242
	v_cmp_eq_u32_e64 s[74:75], 0, v242
	v_writelane_b32 v253, s38, 24
	v_lshlrev_b32_e32 v242, 5, v135
	s_cselect_b32 s60, s5, s4
	v_writelane_b32 v253, s39, 25
	v_cmp_lt_u32_e64 s[38:39], 22, v1
	v_lshrrev_b32_e32 v113, 2, v134
	v_lshlrev_b32_e32 v115, 6, v214
	v_writelane_b32 v253, s38, 26
	v_lshlrev_b32_e32 v38, 6, v134
	v_lshl_add_u64 v[78:79], s[14:15], 0, v[138:139]
	v_writelane_b32 v253, s39, 27
	v_writelane_b32 v253, s48, 28
	v_cmp_eq_u32_e64 s[38:39], 25, v1
	v_or_b32_e32 v80, 0x1000, v136
	v_writelane_b32 v253, s49, 29
	v_cmp_lt_u32_e64 s[48:49], 5, v2
	v_cmp_gt_u32_e64 s[4:5], 32, v135
	v_or_b32_e32 v84, 20, v133
	v_writelane_b32 v253, s48, 30
	v_or_b32_e32 v36, 18, v133
	v_or_b32_e32 v236, 24, v133
	v_writelane_b32 v253, s49, 31
	v_cmp_lt_u32_e64 s[48:49], 6, v2
	v_or_b32_e32 v81, 28, v133
	s_mov_b32 s15, 0
	v_writelane_b32 v253, s48, 32
	v_cmp_lt_u32_e64 s[16:17], 1, v214
	v_cmp_ne_u32_e64 s[26:27], 0, v214
	v_writelane_b32 v253, s49, 33
	v_cmp_lt_u32_e64 s[48:49], 8, v2
	v_cmp_eq_u32_e64 s[28:29], 3, v214
	v_or_b32_e32 v83, 0x101, v88
	v_writelane_b32 v253, s48, 34
	v_or_b32_e32 v90, 0x100, v88
	v_or_b32_e32 v85, 0x103, v88
	v_writelane_b32 v253, s49, 35
	v_cmp_lt_u32_e64 s[48:49], 9, v2
	v_or_b32_e32 v92, 0x102, v88
	v_or_b32_e32 v87, 0x201, v88
	v_writelane_b32 v253, s48, 36
	v_or_b32_e32 v86, 0x200, v88
	v_or_b32_e32 v89, 0x203, v88
	v_writelane_b32 v253, s49, 37
	v_cmp_lt_u32_e64 s[48:49], 10, v2
	v_or_b32_e32 v91, 0x301, v88
	v_or_b32_e32 v98, 0x300, v88
	v_writelane_b32 v253, s48, 38
	v_or_b32_e32 v93, 0x303, v88
; DI void cmp_task(const bf16_t* Z, const bf16_t* KCC, const bf16_t* VCT, bf16_t* OCMP, unsigned* selm, int b, int hk, int tg, int lane) {
;     ...
; #pragma unroll
;         for (int mm = 0; mm < 4; ++mm) {
;             const int jm = 8 * g + 2 * mm + h; const float v = mine[mm]; int rank = 0;
; #pragma unroll
;             for (int T = 0; T < 4; ++T)
; #pragma unroll
;                 for (int m2 = 0; m2 < 4; ++m2) { const int je = 8 * T + 2 * m2;
;                     rank += (ev[T][m2] > v || (ev[T][m2] == v && je < jm)) ? 1 : 0; rank += (od[T][m2] > v || (od[T][m2] == v && je + 1 < jm)) ? 1 : 0; }
;             if (v >= 0.f && rank < 5) word |= 1u << jm;
; __global__ void __launch_bounds__(NTHR, 2) fwd_kernel(Args a) {
;     ...
;         for (int i = 0; i < nrow || ci < ncmp; ++i) {
;             if (ci < ncmp && (i >= nrow || (i % stride) == phase)) { const int task = gw + ci * NGW; ++ci;
;                 cmp_task(Z, KCC, VCT, OCMP, SELM, task >> 9, (task >> 8) & 1, (task + 64 * (task >> 11)) & 255, lane); }
	v_or_b32_e32 v100, 0x302, v88
	v_writelane_b32 v253, s49, 39
	v_cmp_lt_u32_e64 s[48:49], 16, v2
	v_or_b32_e32 v102, 0x400, v88
	v_or_b32_e32 v104, 0x402, v88
	v_writelane_b32 v253, s48, 40
	v_or_b32_e32 v99, 0x501, v88
	v_or_b32_e32 v106, 0x500, v88
	v_writelane_b32 v253, s49, 41
	v_cmp_lt_u32_e64 s[48:49], 12, v2
	v_or_b32_e32 v101, 0x503, v88
	v_or_b32_e32 v108, 0x502, v88
	v_writelane_b32 v253, s48, 42
	v_or_b32_e32 v103, 0x601, v88
	v_or_b32_e32 v110, 0x600, v88
	v_writelane_b32 v253, s49, 43
	v_cmp_lt_u32_e64 s[48:49], 17, v2
	v_or_b32_e32 v105, 0x603, v88
	v_or_b32_e32 v112, 0x602, v88
	v_writelane_b32 v253, s48, 44
	v_or_b32_e32 v107, 0x701, v88
	v_or_b32_e32 v114, 0x700, v88
	v_writelane_b32 v253, s49, 45
	v_cmp_lt_u32_e64 s[48:49], 13, v2
	v_or_b32_e32 v109, 0x703, v88
	v_or_b32_e32 v116, 0x702, v88
	v_writelane_b32 v253, s48, 46
	v_or_b32_e32 v243, 31, v242
	s_mov_b32 s46, 0x3e38aa3b
	v_writelane_b32 v253, s49, 47
	v_cmp_lt_u32_e64 s[48:49], 18, v2
	s_mov_b32 s61, 0xff800000
	s_mov_b32 s62, -1.0
	v_writelane_b32 v253, s48, 48
	v_lshlrev_b32_e32 v120, 2, v88
	v_mov_b32_e32 v244, 0x2200
	v_writelane_b32 v253, s49, 49
	v_cmp_lt_u32_e64 s[48:49], 14, v2
	v_mov_b32_e32 v245, 0xff800000
	s_mov_b32 s63, 0
	v_writelane_b32 v253, s48, 50
	s_mov_b32 s64, 0
	s_nop 0
	v_writelane_b32 v253, s49, 51
	v_cmp_lt_u32_e64 s[48:49], 20, v2
	s_nop 1
	v_writelane_b32 v253, s48, 52
	s_nop 1
	v_writelane_b32 v253, s49, 53
	v_cmp_lt_u32_e64 s[48:49], 21, v2
	s_nop 1
	v_writelane_b32 v253, s48, 54
	s_nop 1
	v_writelane_b32 v253, s49, 55
	v_cmp_lt_u32_e64 s[48:49], 22, v2
	s_nop 1
	v_writelane_b32 v253, s48, 56
	s_nop 1
	v_writelane_b32 v253, s49, 57
	v_cmp_lt_u32_e64 s[48:49], 24, v2
	s_nop 1
	v_writelane_b32 v253, s48, 58
	s_nop 1
	v_writelane_b32 v253, s49, 59
	v_cmp_lt_u32_e64 s[48:49], 25, v2
	v_or_b32_e32 v2, 4, v1
	s_nop 0
	v_writelane_b32 v253, s48, 60
	s_nop 1
	v_writelane_b32 v253, s49, 61
	v_cmp_lt_u32_e64 s[48:49], 5, v2
	s_nop 1
	v_writelane_b32 v253, s48, 62
	s_nop 1
	v_writelane_b32 v253, s49, 63
	v_cmp_lt_u32_e64 s[48:49], 6, v2
	s_nop 1
	v_writelane_b32 v254, s48, 0
	s_nop 1
	v_writelane_b32 v254, s49, 1
	v_cmp_lt_u32_e64 s[48:49], 8, v2
	s_nop 1
	v_writelane_b32 v254, s48, 2
	s_nop 1
	v_writelane_b32 v254, s49, 3
	v_cmp_lt_u32_e64 s[48:49], 9, v2
	s_nop 1
	v_writelane_b32 v254, s48, 4
	s_nop 1
	v_writelane_b32 v254, s49, 5
	v_cmp_lt_u32_e64 s[48:49], 10, v2
	s_nop 1
	v_writelane_b32 v254, s48, 6
	s_nop 1
	v_writelane_b32 v254, s49, 7
	v_cmp_lt_u32_e64 s[48:49], 11, v2
	s_nop 1
	v_writelane_b32 v254, s48, 8
	s_nop 1
	v_writelane_b32 v254, s49, 9
	v_cmp_lt_u32_e64 s[48:49], 12, v2
	s_nop 1
	v_writelane_b32 v254, s48, 10
	s_nop 1
	v_writelane_b32 v254, s49, 11
	v_cmp_lt_u32_e64 s[48:49], 13, v2
	s_nop 1
	v_writelane_b32 v254, s48, 12
	s_nop 1
	v_writelane_b32 v254, s49, 13
	v_cmp_lt_u32_e64 s[48:49], 14, v2
	s_nop 1
	v_writelane_b32 v254, s48, 14
	s_nop 1
	v_writelane_b32 v254, s49, 15
	v_cmp_lt_u32_e64 s[48:49], 16, v2
	s_nop 1
	v_writelane_b32 v254, s48, 16
	s_nop 1
	v_writelane_b32 v254, s49, 17
	v_cmp_lt_u32_e64 s[48:49], 17, v2
	s_nop 1
	v_writelane_b32 v254, s48, 18
	s_nop 1
	v_writelane_b32 v254, s49, 19
	v_cmp_lt_u32_e64 s[48:49], 18, v2
	s_nop 1
	v_writelane_b32 v254, s48, 20
	s_nop 1
	v_writelane_b32 v254, s49, 21
	v_cmp_lt_u32_e64 s[48:49], 19, v2
	s_nop 1
	v_writelane_b32 v254, s48, 22
	s_nop 1
	v_writelane_b32 v254, s49, 23
	v_cmp_lt_u32_e64 s[48:49], 20, v2
	s_nop 1
	v_writelane_b32 v254, s48, 24
	s_nop 1
	v_writelane_b32 v254, s49, 25
	v_cmp_lt_u32_e64 s[48:49], 21, v2
	s_nop 1
	v_writelane_b32 v254, s48, 26
	s_nop 1
	v_writelane_b32 v254, s49, 27
	v_cmp_lt_u32_e64 s[48:49], 22, v2
	s_nop 1
	v_writelane_b32 v254, s48, 28
	s_nop 1
	v_writelane_b32 v254, s49, 29
	v_cmp_lt_u32_e64 s[48:49], 24, v2
	s_nop 1
	v_writelane_b32 v254, s48, 30
	s_nop 1
	v_writelane_b32 v254, s49, 31
	v_cmp_lt_u32_e64 s[48:49], 25, v2
	s_nop 1
	v_writelane_b32 v254, s48, 32
	s_nop 1
	v_writelane_b32 v254, s49, 33
	v_cmp_lt_u32_e64 s[48:49], 26, v2
	s_nop 1
	v_writelane_b32 v254, s48, 34
	s_nop 1
	v_writelane_b32 v254, s49, 35
	v_cmp_lt_u32_e64 s[48:49], 27, v2
	v_or_b32_e32 v2, 6, v1
	v_and_b32_e32 v1, 35, v0
	v_writelane_b32 v254, s48, 36
	v_cmp_lt_u32_e64 s[70:71], 29, v2
	v_cmp_eq_u32_e64 s[72:73], 0, v1
	v_writelane_b32 v254, s49, 37
	v_cmp_lt_u32_e64 s[48:49], 8, v2
	v_mbcnt_lo_u32_b32 v1, -1, 0
	v_mbcnt_hi_u32_b32 v246, -1, v1
	v_writelane_b32 v254, s48, 38
	s_nop 1
	v_writelane_b32 v254, s49, 39
	v_cmp_lt_u32_e64 s[48:49], 9, v2
	s_nop 1
	v_writelane_b32 v254, s48, 40
	s_nop 1
	v_writelane_b32 v254, s49, 41
	v_cmp_lt_u32_e64 s[48:49], 10, v2
	s_nop 1
	v_writelane_b32 v254, s48, 42
	s_nop 1
	v_writelane_b32 v254, s49, 43
	v_cmp_lt_u32_e64 s[48:49], 11, v2
	s_nop 1
	v_writelane_b32 v254, s48, 44
	s_nop 1
	v_writelane_b32 v254, s49, 45
	v_cmp_lt_u32_e64 s[48:49], 12, v2
	s_nop 1
	v_writelane_b32 v254, s48, 46
	s_nop 1
	v_writelane_b32 v254, s49, 47
	v_cmp_lt_u32_e64 s[48:49], 13, v2
	s_nop 1
	v_writelane_b32 v254, s48, 48
	s_nop 1
	v_writelane_b32 v254, s49, 49
	v_cmp_lt_u32_e64 s[48:49], 14, v2
	s_nop 1
	v_writelane_b32 v254, s48, 50
	s_nop 1
	v_writelane_b32 v254, s49, 51
	v_cmp_lt_u32_e64 s[48:49], 16, v2
	s_nop 1
	v_writelane_b32 v254, s48, 52
	s_nop 1
	v_writelane_b32 v254, s49, 53
	v_cmp_lt_u32_e64 s[48:49], 17, v2
	s_nop 1
	v_writelane_b32 v254, s48, 54
	s_nop 1
	v_writelane_b32 v254, s49, 55
	v_cmp_lt_u32_e64 s[48:49], 18, v2
	s_nop 1
	v_writelane_b32 v254, s48, 56
	s_nop 1
	v_writelane_b32 v254, s49, 57
	v_cmp_lt_u32_e64 s[48:49], 19, v2
	s_nop 1
	v_writelane_b32 v254, s48, 58
	s_nop 1
	v_writelane_b32 v254, s49, 59
	v_cmp_lt_u32_e64 s[48:49], 20, v2
	s_nop 1
	v_writelane_b32 v254, s48, 60
	s_nop 1
	v_writelane_b32 v254, s49, 61
	v_cmp_lt_u32_e64 s[48:49], 21, v2
	s_nop 1
	v_writelane_b32 v254, s48, 62
	s_nop 1
	v_writelane_b32 v254, s49, 63
	v_cmp_lt_u32_e64 s[48:49], 22, v2
	s_nop 1
	v_writelane_b32 v255, s48, 0
	s_nop 1
	v_writelane_b32 v255, s49, 1
	v_cmp_lt_u32_e64 s[48:49], 24, v2
	s_nop 1
	v_writelane_b32 v255, s48, 2
	s_nop 1
	v_writelane_b32 v255, s49, 3
	v_cmp_lt_u32_e64 s[48:49], 25, v2
	s_nop 1
	v_writelane_b32 v255, s48, 4
	s_nop 1
	v_writelane_b32 v255, s49, 5
	v_cmp_lt_u32_e64 s[48:49], 26, v2
	s_nop 1
	v_writelane_b32 v255, s48, 6
	s_nop 1
	v_writelane_b32 v255, s49, 7
	v_cmp_lt_u32_e64 s[48:49], 27, v2
	s_nop 1
	v_writelane_b32 v255, s48, 8
	s_nop 1
	v_writelane_b32 v255, s49, 9
	v_cmp_lt_u32_e64 s[48:49], 28, v2
	v_lshlrev_b64 v[2:3], v135, -1
	v_not_b32_e32 v111, v3
	v_writelane_b32 v255, s48, 10
	v_not_b32_e32 v118, v2
	s_nop 0
	v_writelane_b32 v255, s49, 11
	s_mov_b64 s[48:49], exec
	s_mov_b64 exec, 1
	v_mov_b32_e32 v1, 0x20100
	v_mov_b32_e32 v2, 1
	ds_add_rtn_u32 v2, v1, v2
	s_waitcnt lgkmcnt(0)
	v_readfirstlane_b32 s47, v2
	s_mov_b64 exec, s[48:49]
	s_cmpk_lt_u32 s47, 0x80
	s_cselect_b64 s[8:9], -1, 0
	s_branch .LBB0_477
